# P2: second rel-bias table copy at odd dword shift, bias pairs read with 8B-aligned ds_read_b64 instead of ds_read2_b32
# baseline (speedup 1.0000x reference)
; #define LAS __attribute__((address_space(3)))
; #define ATT_QPTR(I, i_) (Z + ((size_t)((I).qslot0() + ((I).isA ? ((wave * 4 + (i_)) >> 3) : 0)) * TT + (I).seq0 + (I).res * (I).Lr + (I).j0 + 16 * ATT_QT(I, i_) + qi) * 64)
;     ...
;     LAS const float* tb = tbl + (kstart + 4 * g - qrel + TBL / 2);
;     ...
;     const int nloc = nA + nB, r0 = tid >> 3, ch = tid & 7;
;     v4u pk[6], pv[6];
;     ...
;     if (nloc <= 0) return;
;     Item cur = decode(0, na0, nA, nb0), nxt = cur;
;     ...
;     bf16x8 q0, q1;
;     { const bf16* qp = ATT_QPTR(cur, 0); q0 = *(const bf16x8*)(qp + g * 8); q1 = *(const bf16x8*)(qp + 32 + g * 8); }
;     asm volatile("" ::: "memory");
;     ATT_ISSUE(cur);
;     int tkey = -1;
;     for (int k = 0; k < nloc; ++k) {
;         __syncthreads();
; #pragma unroll
;         for (int i = 0; i < 6; ++i) { const int row = r0 + 64 * i; *(LAS v4u*)(ldsK + row * KRS + ch * 16) = pk[i]; *(LAS v4u*)(ldsV + row * VRS + ch * 16) = pv[i];
;             if (ch == 0) { const unsigned kp = (unsigned)(cur.j0 - cur.n() + row); const float ninf = -__builtin_inff();
;                 pmt[row] = (kp < (unsigned)(cur.pair ? cur.Lr : cur.Lre)) ? 0.f : ninf;
;                 pmt[NKS_MAX + row] = (cur.pair ? (kp - (unsigned)cur.Lr < (unsigned)cur.Lr) : (kp < (unsigned)cur.Lre)) ? 0.f : ninf; } }
.LBB0_178:
	s_or_b64 exec, exec, s[8:9]
	v_lshlrev_b32_e32 v0, 3, v144
	v_and_b32_e32 v0, 24, v0
	v_mov_b32_e32 v63, v21
	s_movk_i32 s78, 0x90
	s_movk_i32 s79, 0xa0
	v_lshl_add_u32 v175, v117, 4, 0
	v_lshlrev_b32_e32 v148, 2, v116
	v_add_u32_e32 v150, 0, v0
	v_lshl_add_u64 v[152:153], s[20:21], 0, v[62:63]
	v_mul_lo_u32 v0, v151, s78
	v_mul_lo_u32 v63, v151, s79
	s_add_i32 s0, 0, 0x1f000
	v_add_u32_e32 v180, 64, v151
	v_add_u32_e32 v1, 0x2800, v63
	v_add_u32_e32 v182, 0x80, v151
	v_add_u32_e32 v2, 0x5000, v63
	v_add_u32_e32 v184, 0xc0, v151
	v_add_u32_e32 v3, 0x7800, v63
	v_add_u32_e32 v186, 0x100, v151
	v_add_u32_e32 v4, 0xa000, v63
	v_add_u32_e32 v188, 0x140, v151
	v_add_u32_e32 v5, 0xc800, v63
	v_sub_u32_e32 v6, v148, v144
	v_add_u32_e32 v242, 4, v151
	v_bfe_u32 v242, v242, 3, 1
	v_xor_b32_e32 v242, v242, v117
	v_lshl_add_u32 v193, v242, 4, v0
	v_mbcnt_lo_u32_b32 v0, -1, 0
	v_mov_b32_e32 v145, v16
	v_cmp_ne_u32_e64 s[8:9], 0, v117
	s_lshl_b32 s77, s49, 2
	v_add_u32_e32 v243, 4, v144
	v_bfe_u32 v243, v243, 3, 1
	v_xor_b32_e32 v243, v243, v116
	v_lshlrev_b32_e32 v146, 4, v243
	v_and_b32_e32 v253, 1, v144
	v_mul_u32_u24_e32 v253, 0x3884, v253
	v_lshrrev_b32_e32 v178, 2, v144
	v_mov_b32_e32 v149, v21
	v_cmp_eq_u32_e64 s[4:5], 0, v116
	v_lshl_add_u32 v179, v151, 2, s0
	v_lshl_add_u32 v181, v180, 2, s0
	v_lshl_add_u32 v183, v182, 2, s0
	v_lshl_add_u32 v185, v184, 2, s0
	v_lshl_add_u32 v187, v186, 2, s0
	v_lshl_add_u32 v189, v188, 2, s0
	s_lshl_b32 s80, s49, 1
	v_subrev_u32_e32 v190, s73, v6
	s_mov_b32 s66, -1
	s_mov_b32 s81, 0xff800000
	v_add_u32_e32 v191, v175, v2
	v_add_u32_e32 v192, v175, v4
	s_movk_i32 s82, 0x280
	s_add_i32 s83, 0, 0x1c800
	v_add_u32_e32 v194, v175, v1
	v_mov_b32_e32 v195, 0xff800000
	v_add_u32_e32 v197, v175, v3
	v_add_u32_e32 v198, v175, v5
	v_mov_b32_e32 v56, 0
	v_mbcnt_hi_u32_b32 v199, -1, v0
	v_mov_b32_e32 v200, 0x42000000
	s_mov_b32 s84, 0
	s_branch .LBB0_180

;     ...
;             for (int i = tid; i < cur.nh() * TBL; i += 512) { const int h = i / TBL, rel = i % TBL - TBL / 2; const int ar = rel < 0 ? -rel : rel;
;                 tbl[i] = (ar <= cur.n()) ? rel_bias[rel_bucket(rel * cur.dil) * 20 + cur.bcol0() + h] * LOG2E : -__builtin_inff(); } }
.LBB0_199:
	s_or_b64 exec, exec, s[60:61]
	v_add_u32_e32 v2, 0x200, v2
	v_cmp_le_i32_e32 vcc, s1, v2
	ds_write_b32 v1, v5
	ds_write_b32 v1, v5 offset:14468
	v_add_u32_e32 v0, 0xfffffe00, v0
	s_or_b64 s[58:59], vcc, s[58:59]
	v_add_u32_e32 v1, 0x800, v1
	s_andn2_b64 exec, exec, s[58:59]
	s_cbranch_execz .LBB0_206

; #define LAS __attribute__((address_space(3)))
;     ...
;     LAS const float* tb = tbl + (kstart + 4 * g - qrel + TBL / 2);
;     float m = NEG;
;     {
;         float tv[2][8];
; #pragma unroll
;         for (int i = 0; i < 8; ++i) tv[0][i] = tb[16 * (i >> 2) + (i & 3)];
; #pragma unroll
;         for (int tp = 0; tp < NT / 2; ++tp) { const int b = tp & 1;
;             if (tp + 1 < NT / 2) {
; #pragma unroll
;                 for (int i = 0; i < 8; ++i) tv[b ^ 1][i] = tb[16 * (2 * (tp + 1) + (i >> 2)) + (i & 3)]; }
;             __builtin_amdgcn_sched_barrier(0);
; #pragma unroll
;             for (int i = 0; i < 8; ++i) { const int t = 2 * tp + (i >> 2), r = i & 3; const float v = s[t][r] * C + tv[b][i]; s[t][r] = v; m = fmaxf(m, v); }
;             __builtin_amdgcn_sched_barrier(0);
;         }
;     }
;     m = fmaxf(m, __shfl_xor(m, 16)); m = fmaxf(m, __shfl_xor(m, 32));
.LBB0_246:
	s_mulk_i32 s1, 0xa00
	s_add_i32 s1, s1, 0
	v_or_b32_e32 v158, s0, v144
	s_add_i32 s1, s1, 0x1c800
	v_sub_u32_e32 v158, v205, v158
	v_lshl_add_u32 v177, v158, 2, s1
	v_add_u32_e32 v177, v177, v253
	ds_read_b64 v[172:173], v177 offset:768
	ds_read_b64 v[170:171], v177 offset:776
	ds_read_b64 v[168:169], v177 offset:832
	ds_read_b64 v[166:167], v177 offset:840
	ds_read_b64 v[164:165], v177 offset:896
	ds_read_b64 v[162:163], v177 offset:904
	ds_read_b64 v[160:161], v177 offset:960
	ds_read_b64 v[158:159], v177 offset:968
	v_add_u32_e32 v20, s0, v201
	v_mov_b64_e32 v[156:157], s[16:17]
	s_movk_i32 s0, 0x300
	v_mad_i64_i32 v[156:157], s[0:1], v20, s0, v[156:157]
	s_lshl_b32 s0, s64, 6
	s_ashr_i32 s1, s0, 31
	v_mul_f32_e32 v176, 0x3fb8aa3b, v204
	v_lshl_add_u64 v[156:157], v[156:157], 0, s[0:1]
	s_mov_b32 s0, 0x3e38aa3b
	s_mov_b32 s1, s0
	v_add_u32_e32 v196, 0x400, v177
	s_waitcnt lgkmcnt(7)
	v_pk_fma_f32 v[172:173], v[140:141], s[0:1], v[172:173] op_sel_hi:[1,0,1]
	s_waitcnt lgkmcnt(6)
	v_pk_fma_f32 v[170:171], v[142:143], s[0:1], v[170:171] op_sel_hi:[1,0,1]
	v_max3_f32 v20, v172, s81, v173
	s_waitcnt lgkmcnt(5)
	v_pk_fma_f32 v[168:169], v[136:137], s[0:1], v[168:169] op_sel_hi:[1,0,1]
	v_max3_f32 v20, v20, v170, v171
	s_waitcnt lgkmcnt(4)
	v_pk_fma_f32 v[166:167], v[138:139], s[0:1], v[166:167] op_sel_hi:[1,0,1]
	v_max3_f32 v20, v20, v168, v169
	ds_read_b64 v[142:143], v196 offset:0
	ds_read_b64 v[140:141], v196 offset:8
	ds_read_b64 v[138:139], v196 offset:64
	ds_read_b64 v[136:137], v196 offset:72
	s_waitcnt lgkmcnt(7)
	v_pk_fma_f32 v[164:165], v[132:133], s[0:1], v[164:165] op_sel_hi:[1,0,1]
	v_max3_f32 v20, v20, v166, v167
	s_waitcnt lgkmcnt(6)
	v_pk_fma_f32 v[162:163], v[134:135], s[0:1], v[162:163] op_sel_hi:[1,0,1]
	v_max3_f32 v20, v20, v164, v165
	s_waitcnt lgkmcnt(5)
	v_pk_fma_f32 v[160:161], v[128:129], s[0:1], v[160:161] op_sel_hi:[1,0,1]
	v_max3_f32 v20, v20, v162, v163
	s_waitcnt lgkmcnt(4)
	v_pk_fma_f32 v[158:159], v[130:131], s[0:1], v[158:159] op_sel_hi:[1,0,1]
	v_max3_f32 v20, v20, v160, v161
	ds_read_b64 v[134:135], v196 offset:128
	ds_read_b64 v[132:133], v196 offset:136
	ds_read_b64 v[130:131], v196 offset:192
	ds_read_b64 v[128:129], v196 offset:200
	s_waitcnt lgkmcnt(7)
	v_pk_fma_f32 v[142:143], v[124:125], s[0:1], v[142:143] op_sel_hi:[1,0,1]
	v_max3_f32 v20, v20, v158, v159
	s_waitcnt lgkmcnt(6)
	v_pk_fma_f32 v[140:141], v[126:127], s[0:1], v[140:141] op_sel_hi:[1,0,1]
	v_max3_f32 v20, v20, v142, v143
	s_waitcnt lgkmcnt(5)
	v_pk_fma_f32 v[138:139], v[120:121], s[0:1], v[138:139] op_sel_hi:[1,0,1]
	v_max3_f32 v20, v20, v140, v141
	s_waitcnt lgkmcnt(4)
	v_pk_fma_f32 v[136:137], v[122:123], s[0:1], v[136:137] op_sel_hi:[1,0,1]
	v_max3_f32 v20, v20, v138, v139
	ds_read_b64 v[126:127], v196 offset:256
	ds_read_b64 v[124:125], v196 offset:264
	ds_read_b64 v[122:123], v196 offset:320
	ds_read_b64 v[120:121], v196 offset:328
	s_waitcnt lgkmcnt(7)
	v_pk_fma_f32 v[134:135], v[116:117], s[0:1], v[134:135] op_sel_hi:[1,0,1]
	v_max3_f32 v20, v20, v136, v137
	s_waitcnt lgkmcnt(6)
	v_pk_fma_f32 v[132:133], v[118:119], s[0:1], v[132:133] op_sel_hi:[1,0,1]
	v_max3_f32 v20, v20, v134, v135
	s_waitcnt lgkmcnt(5)
	v_pk_fma_f32 v[130:131], v[88:89], s[0:1], v[130:131] op_sel_hi:[1,0,1]
	v_max3_f32 v20, v20, v132, v133
	s_waitcnt lgkmcnt(4)
	v_pk_fma_f32 v[128:129], v[90:91], s[0:1], v[128:129] op_sel_hi:[1,0,1]
	v_max3_f32 v20, v20, v130, v131
	ds_read_b64 v[118:119], v196 offset:384
	ds_read_b64 v[116:117], v196 offset:392
	ds_read_b64 v[90:91], v196 offset:448
	ds_read_b64 v[88:89], v196 offset:456
	s_waitcnt lgkmcnt(7)
	v_pk_fma_f32 v[126:127], v[84:85], s[0:1], v[126:127] op_sel_hi:[1,0,1]
	v_max3_f32 v20, v20, v128, v129
	s_waitcnt lgkmcnt(6)
	v_pk_fma_f32 v[124:125], v[86:87], s[0:1], v[124:125] op_sel_hi:[1,0,1]
	v_max3_f32 v20, v20, v126, v127
	s_waitcnt lgkmcnt(5)
	v_pk_fma_f32 v[122:123], v[80:81], s[0:1], v[122:123] op_sel_hi:[1,0,1]
	v_max3_f32 v20, v20, v124, v125
	s_waitcnt lgkmcnt(4)
	v_pk_fma_f32 v[120:121], v[82:83], s[0:1], v[120:121] op_sel_hi:[1,0,1]
	v_max3_f32 v20, v20, v122, v123
	ds_read_b64 v[86:87], v196 offset:512
	ds_read_b64 v[84:85], v196 offset:520
	ds_read_b64 v[82:83], v196 offset:576
	ds_read_b64 v[80:81], v196 offset:584
	s_waitcnt lgkmcnt(7)
	v_pk_fma_f32 v[118:119], v[76:77], s[0:1], v[118:119] op_sel_hi:[1,0,1]
	v_max3_f32 v20, v20, v120, v121
	s_waitcnt lgkmcnt(6)
	v_pk_fma_f32 v[116:117], v[78:79], s[0:1], v[116:117] op_sel_hi:[1,0,1]
	v_max3_f32 v20, v20, v118, v119
	s_waitcnt lgkmcnt(5)
	v_pk_fma_f32 v[90:91], v[72:73], s[0:1], v[90:91] op_sel_hi:[1,0,1]
	v_max3_f32 v20, v20, v116, v117
	s_waitcnt lgkmcnt(4)
	v_pk_fma_f32 v[88:89], v[74:75], s[0:1], v[88:89] op_sel_hi:[1,0,1]
	v_max3_f32 v20, v20, v90, v91
	ds_read_b64 v[78:79], v196 offset:640
	ds_read_b64 v[76:77], v196 offset:648
	ds_read_b64 v[74:75], v196 offset:704
	ds_read_b64 v[72:73], v196 offset:712
	s_waitcnt lgkmcnt(7)
	v_pk_fma_f32 v[86:87], v[68:69], s[0:1], v[86:87] op_sel_hi:[1,0,1]
	v_max3_f32 v20, v20, v88, v89
	s_waitcnt lgkmcnt(6)
	v_pk_fma_f32 v[84:85], v[70:71], s[0:1], v[84:85] op_sel_hi:[1,0,1]
	v_max3_f32 v20, v20, v86, v87
	s_waitcnt lgkmcnt(5)
	v_pk_fma_f32 v[82:83], v[52:53], s[0:1], v[82:83] op_sel_hi:[1,0,1]
	v_max3_f32 v20, v20, v84, v85
	s_waitcnt lgkmcnt(4)
	v_pk_fma_f32 v[80:81], v[54:55], s[0:1], v[80:81] op_sel_hi:[1,0,1]
	v_max3_f32 v20, v20, v82, v83
	ds_read_b64 v[70:71], v196 offset:768
	ds_read_b64 v[68:69], v196 offset:776
	ds_read_b64 v[54:55], v196 offset:832
	ds_read_b64 v[52:53], v196 offset:840
	s_waitcnt lgkmcnt(7)
	v_pk_fma_f32 v[78:79], v[48:49], s[0:1], v[78:79] op_sel_hi:[1,0,1]
	v_max3_f32 v20, v20, v80, v81
	s_waitcnt lgkmcnt(6)
;     ...
;             for (int i = 0; i < 8; ++i) { const int t = 2 * tp + (i >> 2), r = i & 3; const float v = s[t][r] * C + tv[b][i]; s[t][r] = v; m = fmaxf(m, v); }
;             __builtin_amdgcn_sched_barrier(0);
;         }
;     }
;     m = fmaxf(m, __shfl_xor(m, 16)); m = fmaxf(m, __shfl_xor(m, 32));
;     if (IS_A) m = fmaxf(m, sink2);
;     float sum = 0.f;
; #pragma unroll
;     for (int t = 0; t < NT; ++t)
; #pragma unroll
;         for (int r = 0; r < 4; ++r) { const float p = __builtin_amdgcn_exp2f(s[t][r] - m); s[t][r] = p; sum += p; }
;     sum += __shfl_xor(sum, 16); sum += __shfl_xor(sum, 32);
;     if (IS_A) sum += __builtin_amdgcn_exp2f(sink2 - m);
	v_pk_fma_f32 v[76:77], v[50:51], s[0:1], v[76:77] op_sel_hi:[1,0,1]
	v_max3_f32 v20, v20, v78, v79
	s_waitcnt lgkmcnt(5)
	v_pk_fma_f32 v[74:75], v[16:17], s[0:1], v[74:75] op_sel_hi:[1,0,1]
	v_max3_f32 v20, v20, v76, v77
	s_waitcnt lgkmcnt(4)
	v_pk_fma_f32 v[72:73], v[18:19], s[0:1], v[72:73] op_sel_hi:[1,0,1]
	v_max3_f32 v20, v20, v74, v75
	s_waitcnt lgkmcnt(3)
	v_pk_fma_f32 v[70:71], v[12:13], s[0:1], v[70:71] op_sel_hi:[1,0,1]
	v_max3_f32 v20, v20, v72, v73
	s_waitcnt lgkmcnt(2)
	v_pk_fma_f32 v[68:69], v[14:15], s[0:1], v[68:69] op_sel_hi:[1,0,1]
	v_max3_f32 v20, v20, v70, v71
	s_waitcnt lgkmcnt(1)
	v_pk_fma_f32 v[54:55], v[8:9], s[0:1], v[54:55] op_sel_hi:[1,0,1]
	v_max3_f32 v20, v20, v68, v69
	s_waitcnt lgkmcnt(0)
	v_pk_fma_f32 v[52:53], v[10:11], s[0:1], v[52:53] op_sel_hi:[1,0,1]
	v_max3_f32 v20, v20, v54, v55
	v_max3_f32 v20, v20, v52, v53
	v_mov_b32_e32 v252, v20
	s_nop 1
	v_permlane16_swap_b32_e32 v20, v252
	s_nop 0
	v_max_f32_e32 v20, v20, v252
	v_mov_b32_e32 v252, v20
	s_nop 1
	v_permlane32_swap_b32_e32 v20, v252
	s_nop 0
	v_max3_f32 v8, v20, v252, v176
	v_xor_b32_e32 v250, 0x80000000, v8
	v_pk_add_f32 v[172:173], v[172:173], v[250:251] op_sel_hi:[1,0]
	v_exp_f32_e32 v172, v172
	v_exp_f32_e32 v173, v173
	v_pk_add_f32 v[170:171], v[170:171], v[250:251] op_sel_hi:[1,0]
	v_exp_f32_e32 v170, v170
	v_exp_f32_e32 v171, v171
	v_pk_add_f32 v[168:169], v[168:169], v[250:251] op_sel_hi:[1,0]
	v_exp_f32_e32 v168, v168
	v_exp_f32_e32 v169, v169
	v_pk_add_f32 v[248:249], v[172:173], v[170:171]
	v_pk_add_f32 v[166:167], v[166:167], v[250:251] op_sel_hi:[1,0]
	v_exp_f32_e32 v166, v166
	v_exp_f32_e32 v167, v167
	v_pk_add_f32 v[248:249], v[248:249], v[168:169]
	v_pk_add_f32 v[164:165], v[164:165], v[250:251] op_sel_hi:[1,0]
	v_exp_f32_e32 v164, v164
	v_exp_f32_e32 v165, v165
	v_pk_add_f32 v[248:249], v[248:249], v[166:167]
	v_pk_add_f32 v[162:163], v[162:163], v[250:251] op_sel_hi:[1,0]
	v_exp_f32_e32 v162, v162
	v_exp_f32_e32 v163, v163
	v_pk_add_f32 v[248:249], v[248:249], v[164:165]
	v_pk_add_f32 v[160:161], v[160:161], v[250:251] op_sel_hi:[1,0]
	v_exp_f32_e32 v160, v160
	v_exp_f32_e32 v161, v161
	v_pk_add_f32 v[248:249], v[248:249], v[162:163]
	v_pk_add_f32 v[158:159], v[158:159], v[250:251] op_sel_hi:[1,0]
	v_exp_f32_e32 v158, v158
	v_exp_f32_e32 v159, v159
	v_pk_add_f32 v[248:249], v[248:249], v[160:161]
	v_pk_add_f32 v[142:143], v[142:143], v[250:251] op_sel_hi:[1,0]
	v_exp_f32_e32 v142, v142
	v_exp_f32_e32 v143, v143
	v_pk_add_f32 v[248:249], v[248:249], v[158:159]
	v_pk_add_f32 v[140:141], v[140:141], v[250:251] op_sel_hi:[1,0]
	v_exp_f32_e32 v140, v140
	v_exp_f32_e32 v141, v141
	v_pk_add_f32 v[248:249], v[248:249], v[142:143]
	v_pk_add_f32 v[138:139], v[138:139], v[250:251] op_sel_hi:[1,0]
	v_exp_f32_e32 v138, v138
	v_exp_f32_e32 v139, v139
	v_pk_add_f32 v[248:249], v[248:249], v[140:141]
	v_pk_add_f32 v[136:137], v[136:137], v[250:251] op_sel_hi:[1,0]
	v_exp_f32_e32 v136, v136
	v_exp_f32_e32 v137, v137
	v_pk_add_f32 v[248:249], v[248:249], v[138:139]
	v_pk_add_f32 v[134:135], v[134:135], v[250:251] op_sel_hi:[1,0]
	v_exp_f32_e32 v134, v134
	v_exp_f32_e32 v135, v135
	v_pk_add_f32 v[248:249], v[248:249], v[136:137]
	v_pk_add_f32 v[132:133], v[132:133], v[250:251] op_sel_hi:[1,0]
	v_exp_f32_e32 v132, v132
	v_exp_f32_e32 v133, v133
	v_pk_add_f32 v[248:249], v[248:249], v[134:135]
	v_pk_add_f32 v[130:131], v[130:131], v[250:251] op_sel_hi:[1,0]
	v_exp_f32_e32 v130, v130
	v_exp_f32_e32 v131, v131
	v_pk_add_f32 v[248:249], v[248:249], v[132:133]
	v_pk_add_f32 v[128:129], v[128:129], v[250:251] op_sel_hi:[1,0]
	v_exp_f32_e32 v128, v128
	v_exp_f32_e32 v129, v129
	v_pk_add_f32 v[248:249], v[248:249], v[130:131]
	v_pk_add_f32 v[126:127], v[126:127], v[250:251] op_sel_hi:[1,0]
	v_exp_f32_e32 v176, v126
	v_exp_f32_e32 v177, v127
	v_pk_add_f32 v[248:249], v[248:249], v[128:129]
	v_pk_add_f32 v[124:125], v[124:125], v[250:251] op_sel_hi:[1,0]
	v_exp_f32_e32 v206, v124
	v_exp_f32_e32 v207, v125
	v_pk_add_f32 v[248:249], v[248:249], v[176:177]
	v_pk_add_f32 v[122:123], v[122:123], v[250:251] op_sel_hi:[1,0]
	v_exp_f32_e32 v208, v122
	v_exp_f32_e32 v209, v123
	v_pk_add_f32 v[248:249], v[248:249], v[206:207]
	v_pk_add_f32 v[120:121], v[120:121], v[250:251] op_sel_hi:[1,0]
	v_exp_f32_e32 v210, v120
	v_exp_f32_e32 v211, v121
	v_pk_add_f32 v[248:249], v[248:249], v[208:209]
	v_pk_add_f32 v[118:119], v[118:119], v[250:251] op_sel_hi:[1,0]
	v_exp_f32_e32 v212, v118
	v_exp_f32_e32 v213, v119
	v_pk_add_f32 v[248:249], v[248:249], v[210:211]
	v_pk_add_f32 v[116:117], v[116:117], v[250:251] op_sel_hi:[1,0]
	v_exp_f32_e32 v214, v116
	v_exp_f32_e32 v215, v117
	v_pk_add_f32 v[248:249], v[248:249], v[212:213]
	v_pk_add_f32 v[90:91], v[90:91], v[250:251] op_sel_hi:[1,0]
	v_exp_f32_e32 v216, v90
	v_exp_f32_e32 v217, v91
	v_pk_add_f32 v[248:249], v[248:249], v[214:215]
	v_pk_add_f32 v[88:89], v[88:89], v[250:251] op_sel_hi:[1,0]
	v_exp_f32_e32 v218, v88
	v_exp_f32_e32 v219, v89
	v_pk_add_f32 v[248:249], v[248:249], v[216:217]
	v_pk_add_f32 v[86:87], v[86:87], v[250:251] op_sel_hi:[1,0]
	v_exp_f32_e32 v220, v86
	v_exp_f32_e32 v221, v87
	v_pk_add_f32 v[248:249], v[248:249], v[218:219]
	v_pk_add_f32 v[84:85], v[84:85], v[250:251] op_sel_hi:[1,0]
	v_exp_f32_e32 v222, v84
	v_exp_f32_e32 v223, v85
	v_pk_add_f32 v[248:249], v[248:249], v[220:221]
	v_pk_add_f32 v[82:83], v[82:83], v[250:251] op_sel_hi:[1,0]
	v_exp_f32_e32 v224, v82
	v_exp_f32_e32 v225, v83
	v_pk_add_f32 v[248:249], v[248:249], v[222:223]
	v_pk_add_f32 v[80:81], v[80:81], v[250:251] op_sel_hi:[1,0]
	v_exp_f32_e32 v226, v80
	v_exp_f32_e32 v227, v81
	v_pk_add_f32 v[248:249], v[248:249], v[224:225]
; #define LAS __attribute__((address_space(3)))
; __device__ __forceinline__ unsigned cvtpk(float lo, float hi) { return pg8::cvt_pk_bf16(lo, hi); }
; __device__ __forceinline__ s16x4 vtr(LAS const unsigned char* p) { return __builtin_bit_cast(s16x4, __builtin_amdgcn_ds_read_tr16_b64_v4i16((LAS s16x4*)p)); }
;     ...
;     sum += __shfl_xor(sum, 16); sum += __shfl_xor(sum, 32);
;     if (IS_A) sum += __builtin_amdgcn_exp2f(sink2 - m);
;     const float inv = __builtin_amdgcn_rcpf(sum);
;     f32x4 o[4];
; #pragma unroll
;     for (int d = 0; d < 4; ++d) o[d] = (f32x4){0.f, 0.f, 0.f, 0.f};
;     LAS const unsigned char* vp = ldsV + (kstart + 4 * g + (qi >> 2)) * VRS + (qi & 3) * 8;
;     {
;         s16x4 vl[2][4], vh[2][4];
; #pragma unroll
;         for (int d = 0; d < 4; ++d) { vl[0][d] = vtr(vp + d * 32); vh[0][d] = vtr(vp + 16 * VRS + d * 32); }
; #pragma unroll
;         for (int c = 0; c < NCH; ++c) { const int b = c & 1;
;             if (c + 1 < NCH) {
; #pragma unroll
;                 for (int d = 0; d < 4; ++d) { vl[b ^ 1][d] = vtr(vp + (32 * (c + 1)) * VRS + d * 32); vh[b ^ 1][d] = vtr(vp + (32 * (c + 1) + 16) * VRS + d * 32); } }
;             v4u pw; pw.x = cvtpk(s[2 * c][0], s[2 * c][1]); pw.y = cvtpk(s[2 * c][2], s[2 * c][3]); pw.z = cvtpk(s[2 * c + 1][0], s[2 * c + 1][1]); pw.w = cvtpk(s[2 * c + 1][2], s[2 * c + 1][3]);
;             const bf16x8 pb = __builtin_bit_cast(bf16x8, pw);
;             __builtin_amdgcn_sched_barrier(0);
; #pragma unroll
;             for (int d = 0; d < 4; ++d) { const s16x4 lo = vl[b][d], hi = vh[b][d];
;                 const bf16x8 va = (bf16x8){lo[0], lo[1], lo[2], lo[3], hi[0], hi[1], hi[2], hi[3]};
;                 o[d] = __builtin_amdgcn_mfma_f32_16x16x32_bf16(va, pb, o[d], 0, 0, 0); }
	v_pk_add_f32 v[78:79], v[78:79], v[250:251] op_sel_hi:[1,0]
	v_exp_f32_e32 v228, v78
	v_exp_f32_e32 v229, v79
	v_pk_add_f32 v[248:249], v[248:249], v[226:227]
	v_pk_add_f32 v[76:77], v[76:77], v[250:251] op_sel_hi:[1,0]
	v_exp_f32_e32 v230, v76
	v_exp_f32_e32 v231, v77
	v_pk_add_f32 v[248:249], v[248:249], v[228:229]
	v_pk_add_f32 v[74:75], v[74:75], v[250:251] op_sel_hi:[1,0]
	v_exp_f32_e32 v232, v74
	v_exp_f32_e32 v233, v75
	v_pk_add_f32 v[248:249], v[248:249], v[230:231]
	v_pk_add_f32 v[72:73], v[72:73], v[250:251] op_sel_hi:[1,0]
	v_exp_f32_e32 v234, v72
	v_exp_f32_e32 v235, v73
	v_pk_add_f32 v[248:249], v[248:249], v[232:233]
	v_pk_add_f32 v[70:71], v[70:71], v[250:251] op_sel_hi:[1,0]
	v_exp_f32_e32 v236, v70
	v_exp_f32_e32 v237, v71
	v_pk_add_f32 v[248:249], v[248:249], v[234:235]
	v_pk_add_f32 v[68:69], v[68:69], v[250:251] op_sel_hi:[1,0]
	v_exp_f32_e32 v242, v68
	v_exp_f32_e32 v243, v69
	v_pk_add_f32 v[248:249], v[248:249], v[236:237]
	v_pk_add_f32 v[54:55], v[54:55], v[250:251] op_sel_hi:[1,0]
	v_exp_f32_e32 v244, v54
	v_exp_f32_e32 v245, v55
	v_pk_add_f32 v[248:249], v[248:249], v[242:243]
	v_pk_add_f32 v[52:53], v[52:53], v[250:251] op_sel_hi:[1,0]
	v_exp_f32_e32 v246, v52
	v_exp_f32_e32 v247, v53
	v_pk_add_f32 v[248:249], v[248:249], v[244:245]
	s_nop 0
	v_pk_add_f32 v[248:249], v[248:249], v[246:247]
	v_add_f32_e32 v239, v248, v249
	v_mov_b32_e32 v252, v239
	v_cvt_pk_bf16_f32 v84, v172, v173
	v_cvt_pk_bf16_f32 v85, v170, v171
	v_permlane16_swap_b32_e32 v239, v252
	s_nop 0
	v_add_f32_e32 v239, v239, v252
	v_mov_b32_e32 v252, v239
	v_cvt_pk_bf16_f32 v86, v168, v169
	v_cvt_pk_bf16_f32 v87, v166, v167
	v_permlane32_swap_b32_e32 v239, v252
	s_nop 0
	v_add_f32_e32 v239, v239, v252
	v_or_b32_e32 v10, v205, v178
	v_mad_u32_u24 v82, v10, s79, v150
	v_add_u32_e32 v205, 0xd800, v82
	ds_read_b64_tr_b16 v[10:11], v82 offset:55296
	ds_read_b64_tr_b16 v[14:15], v82 offset:55328
	ds_read_b64_tr_b16 v[48:49], v82 offset:55360
	ds_read_b64_tr_b16 v[52:53], v82 offset:55392
	ds_read_b64_tr_b16 v[12:13], v82 offset:57856
	ds_read_b64_tr_b16 v[16:17], v82 offset:57888
	ds_read_b64_tr_b16 v[50:51], v82 offset:57920
	ds_read_b64_tr_b16 v[54:55], v82 offset:57952
	ds_read_b64_tr_b16 v[68:69], v82 offset:60416
	ds_read_b64_tr_b16 v[72:73], v82 offset:60448
	ds_read_b64_tr_b16 v[76:77], v82 offset:60480
	ds_read_b64_tr_b16 v[80:81], v82 offset:60512
	ds_read_b64_tr_b16 v[70:71], v82 offset:62976
	ds_read_b64_tr_b16 v[74:75], v82 offset:63008
	ds_read_b64_tr_b16 v[78:79], v82 offset:63040
	ds_read_b64_tr_b16 v[82:83], v82 offset:63072
	s_waitcnt lgkmcnt(11)
	v_mfma_f32_16x16x32_bf16 v[10:13], v[10:13], v[84:87], 0
	s_waitcnt lgkmcnt(10)
	v_mfma_f32_16x16x32_bf16 v[14:17], v[14:17], v[84:87], 0
	s_waitcnt lgkmcnt(9)
	v_mfma_f32_16x16x32_bf16 v[48:51], v[48:51], v[84:87], 0
	s_waitcnt lgkmcnt(8)
	v_mfma_f32_16x16x32_bf16 v[52:55], v[52:55], v[84:87], 0
	ds_read_b64_tr_b16 v[84:85], v205 offset:10240
	ds_read_b64_tr_b16 v[88:89], v205 offset:10272
	ds_read_b64_tr_b16 v[116:117], v205 offset:10304
	ds_read_b64_tr_b16 v[120:121], v205 offset:10336
	ds_read_b64_tr_b16 v[86:87], v205 offset:12800
	ds_read_b64_tr_b16 v[90:91], v205 offset:12832
	ds_read_b64_tr_b16 v[118:119], v205 offset:12864
	ds_read_b64_tr_b16 v[122:123], v205 offset:12896
	v_cvt_pk_bf16_f32 v124, v164, v165
	v_cvt_pk_bf16_f32 v125, v162, v163
	v_cvt_pk_bf16_f32 v126, v160, v161
	v_cvt_pk_bf16_f32 v127, v158, v159
	s_waitcnt lgkmcnt(11)
	s_nop 0
	v_mfma_f32_16x16x32_bf16 v[10:13], v[68:71], v[124:127], v[10:13]
	s_waitcnt lgkmcnt(10)
	v_mfma_f32_16x16x32_bf16 v[14:17], v[72:75], v[124:127], v[14:17]
	s_waitcnt lgkmcnt(9)
	v_mfma_f32_16x16x32_bf16 v[48:51], v[76:79], v[124:127], v[48:51]
	s_waitcnt lgkmcnt(8)
	v_mfma_f32_16x16x32_bf16 v[52:55], v[80:83], v[124:127], v[52:55]
	ds_read_b64_tr_b16 v[68:69], v205 offset:15360
	ds_read_b64_tr_b16 v[72:73], v205 offset:15392
	ds_read_b64_tr_b16 v[76:77], v205 offset:15424
	ds_read_b64_tr_b16 v[80:81], v205 offset:15456
	ds_read_b64_tr_b16 v[70:71], v205 offset:17920
	ds_read_b64_tr_b16 v[74:75], v205 offset:17952
	ds_read_b64_tr_b16 v[78:79], v205 offset:17984
	ds_read_b64_tr_b16 v[82:83], v205 offset:18016
	v_cvt_pk_bf16_f32 v124, v142, v143
	v_cvt_pk_bf16_f32 v125, v140, v141
	v_cvt_pk_bf16_f32 v126, v138, v139
	v_cvt_pk_bf16_f32 v127, v136, v137
	s_waitcnt lgkmcnt(11)
	s_nop 0
	v_mfma_f32_16x16x32_bf16 v[10:13], v[84:87], v[124:127], v[10:13]
	s_waitcnt lgkmcnt(10)
	v_mfma_f32_16x16x32_bf16 v[14:17], v[88:91], v[124:127], v[14:17]
	s_waitcnt lgkmcnt(9)
	v_mfma_f32_16x16x32_bf16 v[48:51], v[116:119], v[124:127], v[48:51]
	s_waitcnt lgkmcnt(8)
	v_mfma_f32_16x16x32_bf16 v[52:55], v[120:123], v[124:127], v[52:55]
	ds_read_b64_tr_b16 v[84:85], v205 offset:20480
	ds_read_b64_tr_b16 v[88:89], v205 offset:20512
	ds_read_b64_tr_b16 v[116:117], v205 offset:20544
	ds_read_b64_tr_b16 v[120:121], v205 offset:20576
	ds_read_b64_tr_b16 v[86:87], v205 offset:23040
	ds_read_b64_tr_b16 v[90:91], v205 offset:23072
	ds_read_b64_tr_b16 v[118:119], v205 offset:23104
	ds_read_b64_tr_b16 v[122:123], v205 offset:23136
	v_cvt_pk_bf16_f32 v124, v134, v135
	v_cvt_pk_bf16_f32 v125, v132, v133
	v_cvt_pk_bf16_f32 v126, v130, v131
	v_cvt_pk_bf16_f32 v127, v128, v129
	s_waitcnt lgkmcnt(11)
	s_nop 0
	v_mfma_f32_16x16x32_bf16 v[10:13], v[68:71], v[124:127], v[10:13]
	s_waitcnt lgkmcnt(10)
	v_mfma_f32_16x16x32_bf16 v[14:17], v[72:75], v[124:127], v[14:17]
	s_waitcnt lgkmcnt(9)
	v_mfma_f32_16x16x32_bf16 v[48:51], v[76:79], v[124:127], v[48:51]
	s_waitcnt lgkmcnt(8)
; __device__ __forceinline__ unsigned cvtpk(float lo, float hi) { return pg8::cvt_pk_bf16(lo, hi); }
; __device__ __forceinline__ unsigned pk4_fp8(float a, float b, float c, float d) { int r = __builtin_amdgcn_cvt_pk_fp8_f32(a, b, 0, false); r = __builtin_amdgcn_cvt_pk_fp8_f32(c, d, r, true); return (unsigned)r; }
; __device__ __forceinline__ s16x4 vtr(LAS const unsigned char* p) { return __builtin_bit_cast(s16x4, __builtin_amdgcn_ds_read_tr16_b64_v4i16((LAS s16x4*)p)); }
;     ...
;     if (IS_A) sum += __builtin_amdgcn_exp2f(sink2 - m);
;     const float inv = __builtin_amdgcn_rcpf(sum);
;     ...
;         for (int c = 0; c < NCH; ++c) { const int b = c & 1;
;             if (c + 1 < NCH) {
; #pragma unroll
;                 for (int d = 0; d < 4; ++d) { vl[b ^ 1][d] = vtr(vp + (32 * (c + 1)) * VRS + d * 32); vh[b ^ 1][d] = vtr(vp + (32 * (c + 1) + 16) * VRS + d * 32); } }
;             v4u pw; pw.x = cvtpk(s[2 * c][0], s[2 * c][1]); pw.y = cvtpk(s[2 * c][2], s[2 * c][3]); pw.z = cvtpk(s[2 * c + 1][0], s[2 * c + 1][1]); pw.w = cvtpk(s[2 * c + 1][2], s[2 * c + 1][3]);
;             const bf16x8 pb = __builtin_bit_cast(bf16x8, pw);
;             __builtin_amdgcn_sched_barrier(0);
; #pragma unroll
;             for (int d = 0; d < 4; ++d) { const s16x4 lo = vl[b][d], hi = vh[b][d];
;                 const bf16x8 va = (bf16x8){lo[0], lo[1], lo[2], lo[3], hi[0], hi[1], hi[2], hi[3]};
;                 o[d] = __builtin_amdgcn_mfma_f32_16x16x32_bf16(va, pb, o[d], 0, 0, 0); }
;             __builtin_amdgcn_sched_barrier(0);
;         }
;     }
;     if (IS_A) { const float i8 = inv * 8.f;
; #pragma unroll
;         for (int d = 0; d < 4; ++d) *(unsigned*)((unsigned char*)orow + 16 * d + 4 * g) = pk4_fp8(o[d][0] * i8, o[d][1] * i8, o[d][2] * i8, o[d][3] * i8);
	v_mfma_f32_16x16x32_bf16 v[52:55], v[80:83], v[124:127], v[52:55]
	ds_read_b64_tr_b16 v[68:69], v205 offset:25600
	ds_read_b64_tr_b16 v[72:73], v205 offset:25632
	ds_read_b64_tr_b16 v[76:77], v205 offset:25664
	ds_read_b64_tr_b16 v[80:81], v205 offset:25696
	ds_read_b64_tr_b16 v[70:71], v205 offset:28160
	ds_read_b64_tr_b16 v[74:75], v205 offset:28192
	ds_read_b64_tr_b16 v[78:79], v205 offset:28224
	ds_read_b64_tr_b16 v[82:83], v205 offset:28256
	v_cvt_pk_bf16_f32 v124, v176, v177
	v_cvt_pk_bf16_f32 v125, v206, v207
	v_cvt_pk_bf16_f32 v126, v208, v209
	v_cvt_pk_bf16_f32 v127, v210, v211
	s_waitcnt lgkmcnt(11)
	s_nop 0
	v_mfma_f32_16x16x32_bf16 v[10:13], v[84:87], v[124:127], v[10:13]
	s_waitcnt lgkmcnt(10)
	v_mfma_f32_16x16x32_bf16 v[14:17], v[88:91], v[124:127], v[14:17]
	s_waitcnt lgkmcnt(9)
	v_mfma_f32_16x16x32_bf16 v[48:51], v[116:119], v[124:127], v[48:51]
	s_waitcnt lgkmcnt(8)
	v_mfma_f32_16x16x32_bf16 v[52:55], v[120:123], v[124:127], v[52:55]
	ds_read_b64_tr_b16 v[84:85], v205 offset:30720
	ds_read_b64_tr_b16 v[88:89], v205 offset:30752
	ds_read_b64_tr_b16 v[116:117], v205 offset:30784
	ds_read_b64_tr_b16 v[120:121], v205 offset:30816
	ds_read_b64_tr_b16 v[86:87], v205 offset:33280
	ds_read_b64_tr_b16 v[90:91], v205 offset:33312
	ds_read_b64_tr_b16 v[118:119], v205 offset:33344
	ds_read_b64_tr_b16 v[122:123], v205 offset:33376
	v_cvt_pk_bf16_f32 v124, v212, v213
	v_cvt_pk_bf16_f32 v125, v214, v215
	v_cvt_pk_bf16_f32 v126, v216, v217
	v_cvt_pk_bf16_f32 v127, v218, v219
	s_waitcnt lgkmcnt(11)
	s_nop 0
	v_mfma_f32_16x16x32_bf16 v[10:13], v[68:71], v[124:127], v[10:13]
	s_waitcnt lgkmcnt(10)
	v_mfma_f32_16x16x32_bf16 v[14:17], v[72:75], v[124:127], v[14:17]
	s_waitcnt lgkmcnt(9)
	v_mfma_f32_16x16x32_bf16 v[48:51], v[76:79], v[124:127], v[48:51]
	s_waitcnt lgkmcnt(8)
	v_mfma_f32_16x16x32_bf16 v[52:55], v[80:83], v[124:127], v[52:55]
	ds_read_b64_tr_b16 v[68:69], v205 offset:35840
	ds_read_b64_tr_b16 v[72:73], v205 offset:35872
	ds_read_b64_tr_b16 v[76:77], v205 offset:35904
	ds_read_b64_tr_b16 v[80:81], v205 offset:35936
	ds_read_b64_tr_b16 v[70:71], v205 offset:38400
	ds_read_b64_tr_b16 v[74:75], v205 offset:38432
	ds_read_b64_tr_b16 v[78:79], v205 offset:38464
	ds_read_b64_tr_b16 v[82:83], v205 offset:38496
	v_cvt_pk_bf16_f32 v124, v220, v221
	v_cvt_pk_bf16_f32 v125, v222, v223
	v_cvt_pk_bf16_f32 v126, v224, v225
	v_cvt_pk_bf16_f32 v127, v226, v227
	s_waitcnt lgkmcnt(11)
	s_nop 0
	v_mfma_f32_16x16x32_bf16 v[10:13], v[84:87], v[124:127], v[10:13]
	s_waitcnt lgkmcnt(10)
	v_mfma_f32_16x16x32_bf16 v[14:17], v[88:91], v[124:127], v[14:17]
	s_waitcnt lgkmcnt(9)
	v_mfma_f32_16x16x32_bf16 v[48:51], v[116:119], v[124:127], v[48:51]
	s_waitcnt lgkmcnt(8)
	v_mfma_f32_16x16x32_bf16 v[52:55], v[120:123], v[124:127], v[52:55]
	ds_read_b64_tr_b16 v[84:85], v205 offset:40960
	ds_read_b64_tr_b16 v[88:89], v205 offset:40992
	ds_read_b64_tr_b16 v[116:117], v205 offset:41024
	ds_read_b64_tr_b16 v[120:121], v205 offset:41056
	ds_read_b64_tr_b16 v[86:87], v205 offset:43520
	ds_read_b64_tr_b16 v[90:91], v205 offset:43552
	ds_read_b64_tr_b16 v[118:119], v205 offset:43584
	ds_read_b64_tr_b16 v[122:123], v205 offset:43616
	v_cvt_pk_bf16_f32 v124, v228, v229
	v_cvt_pk_bf16_f32 v125, v230, v231
	v_cvt_pk_bf16_f32 v126, v232, v233
	v_cvt_pk_bf16_f32 v127, v234, v235
	s_waitcnt lgkmcnt(11)
	s_nop 0
	v_mfma_f32_16x16x32_bf16 v[10:13], v[68:71], v[124:127], v[10:13]
	s_waitcnt lgkmcnt(10)
	v_mfma_f32_16x16x32_bf16 v[14:17], v[72:75], v[124:127], v[14:17]
	s_waitcnt lgkmcnt(9)
	v_mfma_f32_16x16x32_bf16 v[48:51], v[76:79], v[124:127], v[48:51]
	s_waitcnt lgkmcnt(8)
	v_mfma_f32_16x16x32_bf16 v[52:55], v[80:83], v[124:127], v[52:55]
	s_mov_b32 s0, 0x3fb8aa3b
	v_fma_f32 v8, v204, s0, -v8
	v_exp_f32_e32 v8, v8
	v_cvt_pk_bf16_f32 v68, v236, v237
	v_cvt_pk_bf16_f32 v69, v242, v243
	v_add_f32_e32 v20, v8, v239
	v_cvt_pk_bf16_f32 v70, v244, v245
	v_cvt_pk_bf16_f32 v71, v246, v247
	s_waitcnt lgkmcnt(3)
	s_nop 0
	v_mfma_f32_16x16x32_bf16 v[8:11], v[84:87], v[68:71], v[10:13]
	s_waitcnt lgkmcnt(2)
	v_mfma_f32_16x16x32_bf16 v[12:15], v[88:91], v[68:71], v[14:17]
	s_waitcnt lgkmcnt(1)
	v_mfma_f32_16x16x32_bf16 v[16:19], v[116:119], v[68:71], v[48:51]
	s_waitcnt lgkmcnt(0)
	v_mfma_f32_16x16x32_bf16 v[48:51], v[120:123], v[68:71], v[52:55]
	v_rcp_f32_e32 v20, v20
	s_nop 1
	v_mov_b32_e32 v54, 0
	v_lshl_add_u64 v[52:53], v[156:157], 0, v[148:149]
	s_mov_b64 s[64:65], 0
	v_mul_f32_e32 v20, 0x41000000, v20
	v_mul_f32_e32 v8, v20, v8
	v_mul_f32_e32 v9, v20, v9
	v_cvt_pk_fp8_f32 v54, v8, v9
	v_mul_f32_e32 v8, v20, v12
	v_mul_f32_e32 v9, v20, v13
	v_mov_b32_e32 v12, 0
	v_cvt_pk_fp8_f32 v12, v8, v9
	v_mul_f32_e32 v8, v20, v14
	v_mul_f32_e32 v9, v20, v15
	v_mov_b32_e32 v13, 0
	v_cvt_pk_fp8_f32 v12, v8, v9 op_sel:[0,0,1]
	v_mul_f32_e32 v8, v20, v16
	v_mul_f32_e32 v9, v20, v17
	v_cvt_pk_fp8_f32 v13, v8, v9
	v_mul_f32_e32 v8, v20, v48
	v_mul_f32_e32 v9, v20, v49
	v_mov_b32_e32 v14, 0
	v_mul_f32_e32 v10, v20, v10
	v_mul_f32_e32 v11, v20, v11
	v_cvt_pk_fp8_f32 v14, v8, v9
	v_cvt_pk_fp8_f32 v54, v10, v11 op_sel:[0,0,1]
	v_mul_f32_e32 v10, v20, v18
	v_mul_f32_e32 v11, v20, v19
	v_cvt_pk_fp8_f32 v13, v10, v11 op_sel:[0,0,1]
	v_mul_f32_e32 v8, v20, v50
	v_mul_f32_e32 v9, v20, v51
	v_cvt_pk_fp8_f32 v14, v8, v9 op_sel:[0,0,1]
	global_store_dword v[52:53], v54, off
	global_store_dword v[52:53], v12, off offset:16
	global_store_dword v[52:53], v13, off offset:32
	global_store_dword v[52:53], v14, off offset:48
	s_waitcnt vmcnt(4)

; #define LAS __attribute__((address_space(3)))
;     ...
;     LAS const float* tb = tbl + (kstart + 4 * g - qrel + TBL / 2);
;     float m = NEG;
;     {
;         float tv[2][8];
; #pragma unroll
;         for (int i = 0; i < 8; ++i) tv[0][i] = tb[16 * (i >> 2) + (i & 3)];
; #pragma unroll
;         for (int tp = 0; tp < NT / 2; ++tp) { const int b = tp & 1;
;             if (tp + 1 < NT / 2) {
; #pragma unroll
;                 for (int i = 0; i < 8; ++i) tv[b ^ 1][i] = tb[16 * (2 * (tp + 1) + (i >> 2)) + (i & 3)]; }
;             __builtin_amdgcn_sched_barrier(0);
; #pragma unroll
;             for (int i = 0; i < 8; ++i) { const int t = 2 * tp + (i >> 2), r = i & 3; const float v = s[t][r] * C + tv[b][i]; s[t][r] = v; m = fmaxf(m, v); }
;             __builtin_amdgcn_sched_barrier(0);
;         }
;     }
;     m = fmaxf(m, __shfl_xor(m, 16)); m = fmaxf(m, __shfl_xor(m, 32));
;     if (IS_A) m = fmaxf(m, sink2);
;     float sum = 0.f;
; #pragma unroll
;     for (int t = 0; t < NT; ++t)
; #pragma unroll
;         for (int r = 0; r < 4; ++r) { const float p = __builtin_amdgcn_exp2f(s[t][r] - m); s[t][r] = p; sum += p; }
.LBB0_252:
	v_and_b32_e32 v20, s91, v89
	v_add_u32_e32 v89, s0, v203
	v_lshl_add_u32 v109, v89, 2, s83
	v_add_u32_e32 v109, 0x400, v109
	v_add_u32_e32 v109, v109, v253
	ds_read_b64 v[110:111], v109 offset:0
	ds_read_b64 v[112:113], v109 offset:8
	ds_read_b64 v[114:115], v109 offset:64
	ds_read_b64 v[116:117], v109 offset:72
	ds_read_b64 v[118:119], v109 offset:128
	ds_read_b64 v[120:121], v109 offset:136
	ds_read_b64 v[122:123], v109 offset:192
	ds_read_b64 v[124:125], v109 offset:200
	v_mul_lo_u32 v20, v20, s45
	v_add3_u32 v88, s92, v20, v88
	v_ashrrev_i32_e32 v89, 31, v88
	v_lshl_add_u64 v[88:89], s[62:63], 0, v[88:89]
	v_lshlrev_b64 v[90:91], 9, v[88:89]
	s_mov_b32 s0, 0x3e38aa3b
	s_mov_b32 s1, s0
	s_waitcnt lgkmcnt(7)
	v_pk_fma_f32 v[110:111], v[84:85], s[0:1], v[110:111] op_sel_hi:[1,0,1]
	s_waitcnt lgkmcnt(6)
	v_pk_fma_f32 v[112:113], v[86:87], s[0:1], v[112:113] op_sel_hi:[1,0,1]
	v_max3_f32 v20, v110, s81, v111
	s_waitcnt lgkmcnt(5)
	v_pk_fma_f32 v[114:115], v[80:81], s[0:1], v[114:115] op_sel_hi:[1,0,1]
	v_max3_f32 v20, v20, v112, v113
	s_waitcnt lgkmcnt(4)
	v_pk_fma_f32 v[116:117], v[82:83], s[0:1], v[116:117] op_sel_hi:[1,0,1]
	v_max3_f32 v20, v20, v114, v115
	ds_read_b64 v[80:81], v109 offset:256
	ds_read_b64 v[82:83], v109 offset:264
	ds_read_b64 v[84:85], v109 offset:320
	ds_read_b64 v[86:87], v109 offset:328
	s_waitcnt lgkmcnt(7)
	v_pk_fma_f32 v[118:119], v[76:77], s[0:1], v[118:119] op_sel_hi:[1,0,1]
	v_max3_f32 v20, v20, v116, v117
	s_waitcnt lgkmcnt(6)
	v_pk_fma_f32 v[120:121], v[78:79], s[0:1], v[120:121] op_sel_hi:[1,0,1]
	v_max3_f32 v20, v20, v118, v119
	s_waitcnt lgkmcnt(5)
	v_pk_fma_f32 v[122:123], v[72:73], s[0:1], v[122:123] op_sel_hi:[1,0,1]
	v_max3_f32 v20, v20, v120, v121
	s_waitcnt lgkmcnt(4)
	v_pk_fma_f32 v[124:125], v[74:75], s[0:1], v[124:125] op_sel_hi:[1,0,1]
	v_max3_f32 v20, v20, v122, v123
	ds_read_b64 v[72:73], v109 offset:384
	ds_read_b64 v[74:75], v109 offset:392
	ds_read_b64 v[76:77], v109 offset:448
	ds_read_b64 v[78:79], v109 offset:456
	s_waitcnt lgkmcnt(7)
	v_pk_fma_f32 v[80:81], v[68:69], s[0:1], v[80:81] op_sel_hi:[1,0,1]
	v_max3_f32 v20, v20, v124, v125
	s_waitcnt lgkmcnt(6)
	v_pk_fma_f32 v[82:83], v[70:71], s[0:1], v[82:83] op_sel_hi:[1,0,1]
	v_max3_f32 v20, v20, v80, v81
	s_waitcnt lgkmcnt(5)
	v_pk_fma_f32 v[84:85], v[52:53], s[0:1], v[84:85] op_sel_hi:[1,0,1]
	v_max3_f32 v20, v20, v82, v83
	s_waitcnt lgkmcnt(4)
	v_pk_fma_f32 v[86:87], v[54:55], s[0:1], v[86:87] op_sel_hi:[1,0,1]
	v_max3_f32 v20, v20, v84, v85
	ds_read_b64 v[52:53], v109 offset:512
	ds_read_b64 v[54:55], v109 offset:520
	ds_read_b64 v[68:69], v109 offset:576
	ds_read_b64 v[70:71], v109 offset:584
	s_waitcnt lgkmcnt(7)
	v_pk_fma_f32 v[72:73], v[48:49], s[0:1], v[72:73] op_sel_hi:[1,0,1]
	v_max3_f32 v20, v20, v86, v87
	s_waitcnt lgkmcnt(6)
	v_pk_fma_f32 v[74:75], v[50:51], s[0:1], v[74:75] op_sel_hi:[1,0,1]
	v_max3_f32 v20, v20, v72, v73
	s_waitcnt lgkmcnt(5)
	v_pk_fma_f32 v[76:77], v[16:17], s[0:1], v[76:77] op_sel_hi:[1,0,1]
	v_max3_f32 v20, v20, v74, v75
	s_waitcnt lgkmcnt(4)
	v_pk_fma_f32 v[78:79], v[18:19], s[0:1], v[78:79] op_sel_hi:[1,0,1]
	v_max3_f32 v20, v20, v76, v77
	s_waitcnt lgkmcnt(3)
	v_pk_fma_f32 v[52:53], v[12:13], s[0:1], v[52:53] op_sel_hi:[1,0,1]
	v_max3_f32 v20, v20, v78, v79
	s_waitcnt lgkmcnt(2)
	v_pk_fma_f32 v[54:55], v[14:15], s[0:1], v[54:55] op_sel_hi:[1,0,1]
	v_max3_f32 v20, v20, v52, v53
	s_waitcnt lgkmcnt(1)
	v_pk_fma_f32 v[68:69], v[8:9], s[0:1], v[68:69] op_sel_hi:[1,0,1]
	v_max3_f32 v20, v20, v54, v55
	s_waitcnt lgkmcnt(0)
	v_pk_fma_f32 v[70:71], v[10:11], s[0:1], v[70:71] op_sel_hi:[1,0,1]
	v_max3_f32 v20, v20, v68, v69
	v_max3_f32 v20, v20, v70, v71
	v_mov_b32_e32 v252, v20
	s_nop 1
	v_permlane16_swap_b32_e32 v20, v252
	s_nop 0
	v_max_f32_e32 v20, v20, v252
	v_mov_b32_e32 v252, v20
	s_nop 1
	v_permlane32_swap_b32_e32 v20, v252
	s_nop 0
	v_max_f32_e32 v8, v20, v252
	v_xor_b32_e32 v250, 0x80000000, v8
	v_pk_add_f32 v[110:111], v[110:111], v[250:251] op_sel_hi:[1,0]
	v_exp_f32_e32 v110, v110
	v_exp_f32_e32 v111, v111
	v_pk_add_f32 v[112:113], v[112:113], v[250:251] op_sel_hi:[1,0]
	v_exp_f32_e32 v112, v112
	v_exp_f32_e32 v113, v113
	v_pk_add_f32 v[114:115], v[114:115], v[250:251] op_sel_hi:[1,0]
	v_exp_f32_e32 v114, v114
	v_exp_f32_e32 v115, v115
	v_pk_add_f32 v[248:249], v[110:111], v[112:113]
	v_pk_add_f32 v[116:117], v[116:117], v[250:251] op_sel_hi:[1,0]
	v_exp_f32_e32 v116, v116
	v_exp_f32_e32 v117, v117
	v_pk_add_f32 v[248:249], v[248:249], v[114:115]
	v_pk_add_f32 v[118:119], v[118:119], v[250:251] op_sel_hi:[1,0]
	v_exp_f32_e32 v164, v118
	v_exp_f32_e32 v165, v119
	v_pk_add_f32 v[248:249], v[248:249], v[116:117]
	v_pk_add_f32 v[120:121], v[120:121], v[250:251] op_sel_hi:[1,0]
	v_exp_f32_e32 v166, v120
	v_exp_f32_e32 v167, v121
	v_pk_add_f32 v[248:249], v[248:249], v[164:165]
	v_pk_add_f32 v[122:123], v[122:123], v[250:251] op_sel_hi:[1,0]
	v_exp_f32_e32 v168, v122
	v_exp_f32_e32 v169, v123
	v_pk_add_f32 v[248:249], v[248:249], v[166:167]
	v_pk_add_f32 v[124:125], v[124:125], v[250:251] op_sel_hi:[1,0]
	v_exp_f32_e32 v170, v124
	v_exp_f32_e32 v171, v125
	v_pk_add_f32 v[248:249], v[248:249], v[168:169]
	v_pk_add_f32 v[80:81], v[80:81], v[250:251] op_sel_hi:[1,0]
	v_exp_f32_e32 v172, v80
	v_exp_f32_e32 v173, v81
	v_pk_add_f32 v[248:249], v[248:249], v[170:171]
	v_pk_add_f32 v[82:83], v[82:83], v[250:251] op_sel_hi:[1,0]
	v_exp_f32_e32 v176, v82
	v_exp_f32_e32 v177, v83
	v_pk_add_f32 v[248:249], v[248:249], v[172:173]
	v_pk_add_f32 v[84:85], v[84:85], v[250:251] op_sel_hi:[1,0]
	v_exp_f32_e32 v204, v84
	v_exp_f32_e32 v205, v85
	v_pk_add_f32 v[248:249], v[248:249], v[176:177]
; #define LAS __attribute__((address_space(3)))
; __device__ __forceinline__ unsigned cvtpk(float lo, float hi) { return pg8::cvt_pk_bf16(lo, hi); }
; __device__ __forceinline__ s16x4 vtr(LAS const unsigned char* p) { return __builtin_bit_cast(s16x4, __builtin_amdgcn_ds_read_tr16_b64_v4i16((LAS s16x4*)p)); }
;     ...
;     for (int t = 0; t < NT; ++t)
; #pragma unroll
;         for (int r = 0; r < 4; ++r) { const float p = __builtin_amdgcn_exp2f(s[t][r] - m); s[t][r] = p; sum += p; }
;     sum += __shfl_xor(sum, 16); sum += __shfl_xor(sum, 32);
;     if (IS_A) sum += __builtin_amdgcn_exp2f(sink2 - m);
;     const float inv = __builtin_amdgcn_rcpf(sum);
;     f32x4 o[4];
; #pragma unroll
;     for (int d = 0; d < 4; ++d) o[d] = (f32x4){0.f, 0.f, 0.f, 0.f};
;     LAS const unsigned char* vp = ldsV + (kstart + 4 * g + (qi >> 2)) * VRS + (qi & 3) * 8;
;     {
;         s16x4 vl[2][4], vh[2][4];
; #pragma unroll
;         for (int d = 0; d < 4; ++d) { vl[0][d] = vtr(vp + d * 32); vh[0][d] = vtr(vp + 16 * VRS + d * 32); }
; #pragma unroll
;         for (int c = 0; c < NCH; ++c) { const int b = c & 1;
;             if (c + 1 < NCH) {
; #pragma unroll
;                 for (int d = 0; d < 4; ++d) { vl[b ^ 1][d] = vtr(vp + (32 * (c + 1)) * VRS + d * 32); vh[b ^ 1][d] = vtr(vp + (32 * (c + 1) + 16) * VRS + d * 32); } }
;             v4u pw; pw.x = cvtpk(s[2 * c][0], s[2 * c][1]); pw.y = cvtpk(s[2 * c][2], s[2 * c][3]); pw.z = cvtpk(s[2 * c + 1][0], s[2 * c + 1][1]); pw.w = cvtpk(s[2 * c + 1][2], s[2 * c + 1][3]);
;             const bf16x8 pb = __builtin_bit_cast(bf16x8, pw);
;             __builtin_amdgcn_sched_barrier(0);
; #pragma unroll
;             for (int d = 0; d < 4; ++d) { const s16x4 lo = vl[b][d], hi = vh[b][d];
;                 const bf16x8 va = (bf16x8){lo[0], lo[1], lo[2], lo[3], hi[0], hi[1], hi[2], hi[3]};
;                 o[d] = __builtin_amdgcn_mfma_f32_16x16x32_bf16(va, pb, o[d], 0, 0, 0); }
	v_pk_add_f32 v[86:87], v[86:87], v[250:251] op_sel_hi:[1,0]
	v_exp_f32_e32 v206, v86
	v_exp_f32_e32 v207, v87
	v_pk_add_f32 v[248:249], v[248:249], v[204:205]
	v_pk_add_f32 v[72:73], v[72:73], v[250:251] op_sel_hi:[1,0]
	v_exp_f32_e32 v208, v72
	v_exp_f32_e32 v209, v73
	v_pk_add_f32 v[248:249], v[248:249], v[206:207]
	v_pk_add_f32 v[74:75], v[74:75], v[250:251] op_sel_hi:[1,0]
	v_exp_f32_e32 v210, v74
	v_exp_f32_e32 v211, v75
	v_pk_add_f32 v[248:249], v[248:249], v[208:209]
	v_pk_add_f32 v[76:77], v[76:77], v[250:251] op_sel_hi:[1,0]
	v_exp_f32_e32 v212, v76
	v_exp_f32_e32 v213, v77
	v_pk_add_f32 v[248:249], v[248:249], v[210:211]
	v_pk_add_f32 v[78:79], v[78:79], v[250:251] op_sel_hi:[1,0]
	v_exp_f32_e32 v214, v78
	v_exp_f32_e32 v215, v79
	v_pk_add_f32 v[248:249], v[248:249], v[212:213]
	v_pk_add_f32 v[52:53], v[52:53], v[250:251] op_sel_hi:[1,0]
	v_exp_f32_e32 v216, v52
	v_exp_f32_e32 v217, v53
	v_pk_add_f32 v[248:249], v[248:249], v[214:215]
	v_pk_add_f32 v[54:55], v[54:55], v[250:251] op_sel_hi:[1,0]
	v_exp_f32_e32 v218, v54
	v_exp_f32_e32 v219, v55
	v_pk_add_f32 v[248:249], v[248:249], v[216:217]
	v_pk_add_f32 v[68:69], v[68:69], v[250:251] op_sel_hi:[1,0]
	v_exp_f32_e32 v220, v68
	v_exp_f32_e32 v221, v69
	v_pk_add_f32 v[248:249], v[248:249], v[218:219]
	v_pk_add_f32 v[70:71], v[70:71], v[250:251] op_sel_hi:[1,0]
	v_exp_f32_e32 v222, v70
	v_exp_f32_e32 v223, v71
	v_pk_add_f32 v[248:249], v[248:249], v[220:221]
	s_nop 0
	v_pk_add_f32 v[248:249], v[248:249], v[222:223]
	v_add_f32_e32 v9, v248, v249
	v_mov_b32_e32 v252, v9
	v_cvt_pk_bf16_f32 v84, v110, v111
	v_cvt_pk_bf16_f32 v85, v112, v113
	v_permlane16_swap_b32_e32 v9, v252
	s_nop 0
	v_add_f32_e32 v9, v9, v252
	v_mov_b32_e32 v252, v9
	v_cvt_pk_bf16_f32 v86, v114, v115
	v_cvt_pk_bf16_f32 v87, v116, v117
	v_permlane32_swap_b32_e32 v9, v252
	s_nop 0
	v_add_f32_e32 v9, v9, v252
	v_or_b32_e32 v10, v108, v178
	v_mad_u64_u32 v[18:19], s[0:1], v10, s79, v[150:151]
	ds_read_b64_tr_b16 v[10:11], v18 offset:55296
	ds_read_b64_tr_b16 v[14:15], v18 offset:55328
	ds_read_b64_tr_b16 v[48:49], v18 offset:55360
	ds_read_b64_tr_b16 v[52:53], v18 offset:55392
	ds_read_b64_tr_b16 v[12:13], v18 offset:57856
	ds_read_b64_tr_b16 v[16:17], v18 offset:57888
	ds_read_b64_tr_b16 v[50:51], v18 offset:57920
	ds_read_b64_tr_b16 v[54:55], v18 offset:57952
	ds_read_b64_tr_b16 v[68:69], v18 offset:60416
	ds_read_b64_tr_b16 v[72:73], v18 offset:60448
	ds_read_b64_tr_b16 v[76:77], v18 offset:60480
	ds_read_b64_tr_b16 v[80:81], v18 offset:60512
	ds_read_b64_tr_b16 v[70:71], v18 offset:62976
	ds_read_b64_tr_b16 v[74:75], v18 offset:63008
	ds_read_b64_tr_b16 v[78:79], v18 offset:63040
	ds_read_b64_tr_b16 v[82:83], v18 offset:63072
	v_add_u32_e32 v19, 0xd800, v18
	s_waitcnt lgkmcnt(11)
	v_mfma_f32_16x16x32_bf16 v[10:13], v[10:13], v[84:87], 0
	s_waitcnt lgkmcnt(10)
	v_mfma_f32_16x16x32_bf16 v[14:17], v[14:17], v[84:87], 0
	s_waitcnt lgkmcnt(9)
	v_mfma_f32_16x16x32_bf16 v[48:51], v[48:51], v[84:87], 0
	s_waitcnt lgkmcnt(8)
	v_mfma_f32_16x16x32_bf16 v[52:55], v[52:55], v[84:87], 0
	ds_read_b64_tr_b16 v[84:85], v19 offset:10240
	ds_read_b64_tr_b16 v[108:109], v19 offset:10272
	ds_read_b64_tr_b16 v[112:113], v19 offset:10304
	ds_read_b64_tr_b16 v[116:117], v19 offset:10336
	ds_read_b64_tr_b16 v[86:87], v19 offset:12800
	ds_read_b64_tr_b16 v[110:111], v19 offset:12832
	ds_read_b64_tr_b16 v[114:115], v19 offset:12864
	ds_read_b64_tr_b16 v[118:119], v19 offset:12896
	v_cvt_pk_bf16_f32 v120, v164, v165
	v_cvt_pk_bf16_f32 v121, v166, v167
	v_cvt_pk_bf16_f32 v122, v168, v169
	v_cvt_pk_bf16_f32 v123, v170, v171
	s_waitcnt lgkmcnt(11)
	s_nop 0
	v_mfma_f32_16x16x32_bf16 v[10:13], v[68:71], v[120:123], v[10:13]
	s_waitcnt lgkmcnt(10)
	v_mfma_f32_16x16x32_bf16 v[14:17], v[72:75], v[120:123], v[14:17]
	s_waitcnt lgkmcnt(9)
; __device__ __forceinline__ unsigned cvtpk(float lo, float hi) { return pg8::cvt_pk_bf16(lo, hi); }
; __device__ __forceinline__ unsigned pk4_fp8(float a, float b, float c, float d) { int r = __builtin_amdgcn_cvt_pk_fp8_f32(a, b, 0, false); r = __builtin_amdgcn_cvt_pk_fp8_f32(c, d, r, true); return (unsigned)r; }
; __device__ __forceinline__ s16x4 vtr(LAS const unsigned char* p) { return __builtin_bit_cast(s16x4, __builtin_amdgcn_ds_read_tr16_b64_v4i16((LAS s16x4*)p)); }
;     ...
;         for (int c = 0; c < NCH; ++c) { const int b = c & 1;
;             if (c + 1 < NCH) {
; #pragma unroll
;                 for (int d = 0; d < 4; ++d) { vl[b ^ 1][d] = vtr(vp + (32 * (c + 1)) * VRS + d * 32); vh[b ^ 1][d] = vtr(vp + (32 * (c + 1) + 16) * VRS + d * 32); } }
;             v4u pw; pw.x = cvtpk(s[2 * c][0], s[2 * c][1]); pw.y = cvtpk(s[2 * c][2], s[2 * c][3]); pw.z = cvtpk(s[2 * c + 1][0], s[2 * c + 1][1]); pw.w = cvtpk(s[2 * c + 1][2], s[2 * c + 1][3]);
;             const bf16x8 pb = __builtin_bit_cast(bf16x8, pw);
;             __builtin_amdgcn_sched_barrier(0);
; #pragma unroll
;             for (int d = 0; d < 4; ++d) { const s16x4 lo = vl[b][d], hi = vh[b][d];
;                 const bf16x8 va = (bf16x8){lo[0], lo[1], lo[2], lo[3], hi[0], hi[1], hi[2], hi[3]};
;                 o[d] = __builtin_amdgcn_mfma_f32_16x16x32_bf16(va, pb, o[d], 0, 0, 0); }
;             __builtin_amdgcn_sched_barrier(0);
;         }
;     }
;     if (IS_A) { const float i8 = inv * 8.f;
; #pragma unroll
;         for (int d = 0; d < 4; ++d) *(unsigned*)((unsigned char*)orow + 16 * d + 4 * g) = pk4_fp8(o[d][0] * i8, o[d][1] * i8, o[d][2] * i8, o[d][3] * i8);
;     } else {
; #pragma unroll
;         for (int d = 0; d < 4; ++d) { v2u w; w.x = cvtpk(o[d][0] * inv, o[d][1] * inv); w.y = cvtpk(o[d][2] * inv, o[d][3] * inv); if (!(abl & 1) || w.x == 0x12345678u) *(v2u*)(orow + 16 * d + 4 * g) = w; } }
;     if (!IS_A) { if (g == 0 && !(abl & 1)) *lsep = m + __builtin_log2f(sum); }
	v_mfma_f32_16x16x32_bf16 v[48:51], v[76:79], v[120:123], v[48:51]
	s_waitcnt lgkmcnt(8)
	v_mfma_f32_16x16x32_bf16 v[52:55], v[80:83], v[120:123], v[52:55]
	ds_read_b64_tr_b16 v[68:69], v19 offset:15360
	ds_read_b64_tr_b16 v[72:73], v19 offset:15392
	ds_read_b64_tr_b16 v[76:77], v19 offset:15424
	ds_read_b64_tr_b16 v[80:81], v19 offset:15456
	ds_read_b64_tr_b16 v[70:71], v19 offset:17920
	ds_read_b64_tr_b16 v[74:75], v19 offset:17952
	ds_read_b64_tr_b16 v[78:79], v19 offset:17984
	ds_read_b64_tr_b16 v[82:83], v19 offset:18016
	v_cvt_pk_bf16_f32 v120, v172, v173
	v_cvt_pk_bf16_f32 v121, v176, v177
	v_cvt_pk_bf16_f32 v122, v204, v205
	v_cvt_pk_bf16_f32 v123, v206, v207
	s_waitcnt lgkmcnt(11)
	s_nop 0
	v_mfma_f32_16x16x32_bf16 v[10:13], v[84:87], v[120:123], v[10:13]
	s_waitcnt lgkmcnt(10)
	v_mfma_f32_16x16x32_bf16 v[14:17], v[108:111], v[120:123], v[14:17]
	s_waitcnt lgkmcnt(9)
	v_mfma_f32_16x16x32_bf16 v[48:51], v[112:115], v[120:123], v[48:51]
	s_waitcnt lgkmcnt(8)
	v_mfma_f32_16x16x32_bf16 v[52:55], v[116:119], v[120:123], v[52:55]
	ds_read_b64_tr_b16 v[84:85], v19 offset:20480
	ds_read_b64_tr_b16 v[108:109], v19 offset:20512
	ds_read_b64_tr_b16 v[112:113], v19 offset:20544
	ds_read_b64_tr_b16 v[116:117], v19 offset:20576
	ds_read_b64_tr_b16 v[86:87], v19 offset:23040
	ds_read_b64_tr_b16 v[110:111], v19 offset:23072
	ds_read_b64_tr_b16 v[114:115], v19 offset:23104
	ds_read_b64_tr_b16 v[118:119], v19 offset:23136
	v_cvt_pk_bf16_f32 v120, v208, v209
	v_cvt_pk_bf16_f32 v121, v210, v211
	v_cvt_pk_bf16_f32 v122, v212, v213
	v_cvt_pk_bf16_f32 v123, v214, v215
	s_waitcnt lgkmcnt(11)
	s_nop 0
	v_mfma_f32_16x16x32_bf16 v[10:13], v[68:71], v[120:123], v[10:13]
	s_waitcnt lgkmcnt(10)
	v_mfma_f32_16x16x32_bf16 v[14:17], v[72:75], v[120:123], v[14:17]
	s_waitcnt lgkmcnt(9)
	v_mfma_f32_16x16x32_bf16 v[48:51], v[76:79], v[120:123], v[48:51]
	s_waitcnt lgkmcnt(8)
	v_mfma_f32_16x16x32_bf16 v[52:55], v[80:83], v[120:123], v[52:55]
	v_cvt_pk_bf16_f32 v68, v216, v217
	v_cvt_pk_bf16_f32 v69, v218, v219
	v_cvt_pk_bf16_f32 v70, v220, v221
	v_cvt_pk_bf16_f32 v71, v222, v223
	s_waitcnt lgkmcnt(3)
	s_nop 0
	v_mfma_f32_16x16x32_bf16 v[10:13], v[84:87], v[68:71], v[10:13]
	s_waitcnt lgkmcnt(2)
	v_mfma_f32_16x16x32_bf16 v[14:17], v[108:111], v[68:71], v[14:17]
	s_waitcnt lgkmcnt(1)
	v_mfma_f32_16x16x32_bf16 v[48:51], v[112:115], v[68:71], v[48:51]
	s_waitcnt lgkmcnt(0)
	v_mfma_f32_16x16x32_bf16 v[52:55], v[116:119], v[68:71], v[52:55]
	v_rcp_f32_e32 v18, v9
	v_lshl_add_u64 v[68:69], v[22:23], 0, v[90:91]
	v_pk_mul_f32 v[10:11], v[18:19], v[10:11] op_sel_hi:[0,1]
	v_pk_mul_f32 v[12:13], v[18:19], v[12:13] op_sel_hi:[0,1]
	v_cvt_pk_bf16_f32 v10, v10, v11
	v_cvt_pk_bf16_f32 v11, v12, v13
	global_store_dwordx2 v[68:69], v[10:11], off
	v_pk_mul_f32 v[10:11], v[18:19], v[14:15] op_sel_hi:[0,1]
	v_pk_mul_f32 v[12:13], v[18:19], v[16:17] op_sel_hi:[0,1]
	v_cvt_pk_bf16_f32 v10, v10, v11
	v_cvt_pk_bf16_f32 v11, v12, v13
	global_store_dwordx2 v[68:69], v[10:11], off offset:32
	v_pk_mul_f32 v[10:11], v[18:19], v[48:49] op_sel_hi:[0,1]
	v_pk_mul_f32 v[12:13], v[18:19], v[50:51] op_sel_hi:[0,1]
	v_cvt_pk_bf16_f32 v10, v10, v11
	v_cvt_pk_bf16_f32 v11, v12, v13
	global_store_dwordx2 v[68:69], v[10:11], off offset:64
	v_pk_mul_f32 v[10:11], v[18:19], v[52:53] op_sel_hi:[0,1]
	v_pk_mul_f32 v[12:13], v[18:19], v[54:55] op_sel_hi:[0,1]
	v_cvt_pk_bf16_f32 v10, v10, v11
	v_cvt_pk_bf16_f32 v11, v12, v13
	global_store_dwordx2 v[68:69], v[10:11], off offset:96
	s_and_saveexec_b64 s[6:7], s[4:5]
	s_cbranch_execz .LBB0_239
	s_mov_b32 s0, 0x800000
	v_cmp_gt_f32_e32 vcc, s0, v9
	s_nop 1
	v_cndmask_b32_e64 v10, 0, 32, vcc
	v_ldexp_f32 v9, v9, v10
	v_log_f32_e32 v9, v9
	v_cndmask_b32_e32 v12, 0, v200, vcc
	v_lshl_add_u64 v[10:11], v[88:89], 4, s[60:61]
	v_sub_f32_e32 v9, v9, v12
	v_add_f32_e32 v8, v8, v9
	global_store_dword v[10:11], v8, off
	s_branch .LBB0_239
